# merge: per-branch gate-value (sigmoid) loads hoisted to the start of the branch into free VGPRs, so their latency hides under the K-loop
# speedup vs baseline: 1.0087x; 1.0047x over previous
; DI void phase_merge(KargPtr p, int l, unsigned char* smem) {
;     ...
;                     for (int g = 0; g < 4; ++g) gv[a][c][g] = *(const u32x2*)(G + (size_t)c * 32 * 1024 + a * 32 + 8 * g);
; #pragma unroll
;             for (int a = 0; a < 2; ++a)
; #pragma unroll
;                 for (int c = 0; c < 2; ++c)
; #pragma unroll
;                     for (int g = 0; g < 4; ++g) {
;                         const unsigned x0 = gv[a][c][g].x, x1 = gv[a][c][g].y;
;                         mer[a][c][4 * g]     += __uint_as_float(x0 << 16) * acc[a][c][4 * g];
;                         mer[a][c][4 * g + 1] += __uint_as_float(x0 & 0xffff0000u) * acc[a][c][4 * g + 1];
;                         mer[a][c][4 * g + 2] += __uint_as_float(x1 << 16) * acc[a][c][4 * g + 2];
;                         mer[a][c][4 * g + 3] += __uint_as_float(x1 & 0xffff0000u) * acc[a][c][4 * g + 3];
;                     }
.LBB0_554:
	s_waitcnt lgkmcnt(0)
	s_add_i32 s5, s5, 1
	s_nop 0
	s_nop 0
	s_cmp_eq_u32 s5, 3
	s_waitcnt vmcnt(15)
	v_lshlrev_b32_e32 v146, 16, v222
	v_and_b32_e32 v147, 0xffff0000, v222
	v_pk_fma_f32 v[112:113], v[52:53], v[146:147], v[112:113]
	v_lshlrev_b32_e32 v52, 16, v223
	v_and_b32_e32 v53, 0xffff0000, v223
	v_pk_fma_f32 v[116:117], v[54:55], v[52:53], v[116:117]
	s_waitcnt vmcnt(14)
	v_lshlrev_b32_e32 v52, 16, v224
	v_and_b32_e32 v53, 0xffff0000, v224
	v_pk_fma_f32 v[110:111], v[56:57], v[52:53], v[110:111]
	v_lshlrev_b32_e32 v52, 16, v225
	v_and_b32_e32 v53, 0xffff0000, v225
	v_pk_fma_f32 v[114:115], v[58:59], v[52:53], v[114:115]
	s_waitcnt vmcnt(13)
	v_lshlrev_b32_e32 v52, 16, v226
	v_and_b32_e32 v53, 0xffff0000, v226
	v_pk_fma_f32 v[106:107], v[60:61], v[52:53], v[106:107]
	v_lshlrev_b32_e32 v52, 16, v227
	v_and_b32_e32 v53, 0xffff0000, v227
	v_pk_fma_f32 v[108:109], v[62:63], v[52:53], v[108:109]
	s_waitcnt vmcnt(12)
	v_lshlrev_b32_e32 v52, 16, v228
	v_and_b32_e32 v53, 0xffff0000, v228
	v_pk_fma_f32 v[104:105], v[64:65], v[52:53], v[104:105]
	v_lshlrev_b32_e32 v52, 16, v229
	v_and_b32_e32 v53, 0xffff0000, v229
	v_pk_fma_f32 v[86:87], v[66:67], v[52:53], v[86:87]
	s_waitcnt vmcnt(11)
	v_lshlrev_b32_e32 v52, 16, v230
	v_and_b32_e32 v53, 0xffff0000, v230
	v_pk_fma_f32 v[80:81], v[36:37], v[52:53], v[80:81]
	v_lshlrev_b32_e32 v36, 16, v231
	v_and_b32_e32 v37, 0xffff0000, v231
	v_pk_fma_f32 v[84:85], v[38:39], v[36:37], v[84:85]
	s_waitcnt vmcnt(10)
	v_lshlrev_b32_e32 v36, 16, v232
	v_and_b32_e32 v37, 0xffff0000, v232
	v_pk_fma_f32 v[78:79], v[40:41], v[36:37], v[78:79]
	v_lshlrev_b32_e32 v36, 16, v233
	v_and_b32_e32 v37, 0xffff0000, v233
	v_pk_fma_f32 v[82:83], v[42:43], v[36:37], v[82:83]
	s_waitcnt vmcnt(9)
	v_lshlrev_b32_e32 v36, 16, v234
	v_and_b32_e32 v37, 0xffff0000, v234
	v_pk_fma_f32 v[74:75], v[44:45], v[36:37], v[74:75]
	v_lshlrev_b32_e32 v36, 16, v235
	v_and_b32_e32 v37, 0xffff0000, v235
	v_pk_fma_f32 v[76:77], v[46:47], v[36:37], v[76:77]
	s_waitcnt vmcnt(8)
	v_lshlrev_b32_e32 v36, 16, v236
	v_and_b32_e32 v37, 0xffff0000, v236
	v_pk_fma_f32 v[72:73], v[48:49], v[36:37], v[72:73]
	v_lshlrev_b32_e32 v36, 16, v237
	v_and_b32_e32 v37, 0xffff0000, v237
	v_pk_fma_f32 v[68:69], v[50:51], v[36:37], v[68:69]
	s_waitcnt vmcnt(7)
	v_lshlrev_b32_e32 v36, 16, v238
	v_and_b32_e32 v37, 0xffff0000, v238
	v_pk_fma_f32 v[126:127], v[20:21], v[36:37], v[126:127]
	v_lshlrev_b32_e32 v20, 16, v239
	v_and_b32_e32 v21, 0xffff0000, v239
	v_pk_fma_f32 v[130:131], v[22:23], v[20:21], v[130:131]
	s_waitcnt vmcnt(6)
	v_lshlrev_b32_e32 v20, 16, v240
	v_and_b32_e32 v21, 0xffff0000, v240
	v_pk_fma_f32 v[124:125], v[24:25], v[20:21], v[124:125]
	v_lshlrev_b32_e32 v20, 16, v241
	v_and_b32_e32 v21, 0xffff0000, v241
	v_pk_fma_f32 v[128:129], v[26:27], v[20:21], v[128:129]
	s_waitcnt vmcnt(5)
	v_lshlrev_b32_e32 v20, 16, v242
	v_and_b32_e32 v21, 0xffff0000, v242
	v_pk_fma_f32 v[120:121], v[28:29], v[20:21], v[120:121]
	v_lshlrev_b32_e32 v20, 16, v243
	v_and_b32_e32 v21, 0xffff0000, v243
	v_pk_fma_f32 v[122:123], v[30:31], v[20:21], v[122:123]
	s_waitcnt vmcnt(4)
	v_lshlrev_b32_e32 v20, 16, v244
	v_and_b32_e32 v21, 0xffff0000, v244
	v_pk_fma_f32 v[118:119], v[32:33], v[20:21], v[118:119]
	v_lshlrev_b32_e32 v20, 16, v245
	v_and_b32_e32 v21, 0xffff0000, v245
	v_pk_fma_f32 v[102:103], v[34:35], v[20:21], v[102:103]
	s_waitcnt vmcnt(3)
	v_lshlrev_b32_e32 v20, 16, v246
	v_and_b32_e32 v21, 0xffff0000, v246
	v_pk_fma_f32 v[96:97], v[4:5], v[20:21], v[96:97]
	v_lshlrev_b32_e32 v4, 16, v247
	v_and_b32_e32 v5, 0xffff0000, v247
	v_pk_fma_f32 v[100:101], v[6:7], v[4:5], v[100:101]
	s_waitcnt vmcnt(2)
	v_lshlrev_b32_e32 v4, 16, v248
	v_and_b32_e32 v5, 0xffff0000, v248
	v_pk_fma_f32 v[94:95], v[8:9], v[4:5], v[94:95]
	v_lshlrev_b32_e32 v4, 16, v249
	v_and_b32_e32 v5, 0xffff0000, v249
	v_pk_fma_f32 v[98:99], v[10:11], v[4:5], v[98:99]
	s_waitcnt vmcnt(1)
	v_lshlrev_b32_e32 v4, 16, v250
	v_and_b32_e32 v5, 0xffff0000, v250
	v_pk_fma_f32 v[90:91], v[12:13], v[4:5], v[90:91]
	v_lshlrev_b32_e32 v4, 16, v251
	v_and_b32_e32 v5, 0xffff0000, v251
	v_pk_fma_f32 v[92:93], v[14:15], v[4:5], v[92:93]
	s_waitcnt vmcnt(0)
	v_lshlrev_b32_e32 v4, 16, v252
	v_and_b32_e32 v5, 0xffff0000, v252
	v_pk_fma_f32 v[88:89], v[16:17], v[4:5], v[88:89]
	v_lshlrev_b32_e32 v4, 16, v253
	v_and_b32_e32 v5, 0xffff0000, v253
	v_pk_fma_f32 v[70:71], v[18:19], v[4:5], v[70:71]
	s_cbranch_scc1 .LBB0_550
; #define GEMM_STAGE(D_) do { unsigned char* d_ = (D_); \
;         *(u32x4*)(d_) = ra0; *(u32x4*)(d_ + OPB) = rb0; *(u32x4*)(d_ + PASSB) = ra1; *(u32x4*)(d_ + OPB + PASSB) = rb1; \
;         if constexpr (NJ == 4) { *(u32x4*)(d_ + 2 * PASSB) = ra2; *(u32x4*)(d_ + OPB + 2 * PASSB) = rb2; *(u32x4*)(d_ + 3 * PASSB) = ra3; *(u32x4*)(d_ + OPB + 3 * PASSB) = rb3; } } while (0)
; template <int BK>
; DI void gemm_mainloop(const bf16_t* A, int lda, const bf16_t* B, int ldb, int K, f32x16 (&acc)[2][2], unsigned char* smem) {
;     ...
;     const int lrow = tid / CPR, lcol = (tid % CPR) * 8;
;     const bf16_t* ap = A + (size_t)lrow * lda + lcol;
;     const bf16_t* bp = B + (size_t)lrow * ldb + lcol;
;     const size_t astep = (size_t)RPP * lda, bstep = (size_t)RPP * ldb;
;     const int st_off = lrow * ROWB + (tid % CPR) * 16;
;     u32x4 ra0, ra1, ra2, ra3, rb0, rb1, rb2, rb3;
;     ra0 = *(const u32x4*)(ap); rb0 = *(const u32x4*)(bp);
;     ra1 = *(const u32x4*)(ap + astep); rb1 = *(const u32x4*)(bp + bstep);
;     if constexpr (NJ == 4) { ra2 = *(const u32x4*)(ap + 2 * astep); rb2 = *(const u32x4*)(bp + 2 * bstep); ra3 = *(const u32x4*)(ap + 3 * astep); rb3 = *(const u32x4*)(bp + 3 * bstep); }
;     else { ra2 = ra0; ra3 = ra0; rb2 = rb0; rb3 = rb0; }
;     ...
;     GEMM_STAGE(smem + st_off);
;     __syncthreads();
; DI void phase_merge(KargPtr p, int l, unsigned char* smem) {
;     ...
;         for (int br = 0; br < 3; ++br) {
;             f32x16 acc[2][2]; zero_acc(acc);
;             const bf16_t* Y = (br == 0 ? p->qf : br == 1 ? p->qn : p->qs) + (size_t)m0 * 512;
;             const bf16_t* WO = WL + (br == 0 ? W_OF : br == 1 ? W_OM : W_OS) + (size_t)nt * 128 * 512;
;             gemm_mainloop<64>(WO, 512, Y, 512, 512, acc, smem);
;             const bf16_t* G = (br == 0 ? p->gs0 : p->gs1 + (size_t)(br - 1) * T_TOK * 1024) + (size_t)(m0 + wn * 64 + r) * 1024 + nt * 128 + wm * 64 + 4 * hh;
;             u32x2 gv[2][2][4];
; #pragma unroll
;             for (int a = 0; a < 2; ++a)
; #pragma unroll
;                 for (int c = 0; c < 2; ++c)
; #pragma unroll
;                     for (int g = 0; g < 4; ++g) gv[a][c][g] = *(const u32x2*)(G + (size_t)c * 32 * 1024 + a * 32 + 8 * g);
.LBB0_555:
	s_cmp_lg_u32 s5, 0
	s_cselect_b64 s[12:13], -1, 0
	s_cmp_eq_u32 s5, 1
	s_movk_i32 s14, 0x128
	s_mov_b32 s15, 0x7e8000
	s_cselect_b32 s14, s14, 0xf8
	s_cselect_b32 s15, s15, 0x868000
	s_cmp_eq_u32 s5, 0
	s_cselect_b32 s14, 0xe0, s14
	s_cselect_b32 s19, 0x768000, s15
	s_add_u32 s14, s0, s14
	s_addc_u32 s15, s1, 0
	s_load_dwordx2 s[14:15], s[14:15], 0x0
	s_cmp_eq_u32 s5, 0
	s_movk_i32 s24, 0x170
	s_cselect_b32 s24, 0x168, s24
	s_add_u32 s24, s0, s24
	s_addc_u32 s25, s1, 0
	s_load_dwordx2 s[22:23], s[24:25], 0x0
	s_add_i32 s24, s5, -1
	s_max_i32 s24, s24, 0
	s_mov_b32 s25, 0
	s_lshl_b64 s[24:25], s[24:25], 26
	v_mov_b32_e32 v48, v199
	v_mov_b32_e32 v10, v167
	v_ashrrev_i32_e32 v4, 31, v48
	v_lshrrev_b32_e32 v4, 29, v4
	v_add_u32_e32 v4, v48, v4
	s_waitcnt lgkmcnt(0)
	s_add_u32 s14, s14, s10
	v_ashrrev_i32_e32 v46, 3, v4
	v_and_b32_e32 v4, -8, v4
	s_addc_u32 s15, s15, s11
	s_lshl_b32 s19, s19, 1
	v_sub_u32_e32 v49, v48, v4
	s_add_u32 s20, s17, s19
	v_lshlrev_b32_e32 v4, 3, v49
	v_ashrrev_i32_e32 v47, 31, v46
	s_addc_u32 s21, s18, 0
	s_add_u32 s22, s22, s24
	s_addc_u32 s23, s23, s25
	v_lshlrev_b64 v[6:7], 10, v[46:47]
	v_ashrrev_i32_e32 v5, 31, v4
	v_lshl_add_u64 v[8:9], s[20:21], 0, v[6:7]
	v_lshlrev_b64 v[4:5], 1, v[4:5]
	v_lshl_add_u64 v[134:135], v[8:9], 0, v[4:5]
	v_lshl_add_u64 v[6:7], s[14:15], 0, v[6:7]
	v_lshl_add_u64 v[136:137], v[6:7], 0, v[4:5]
	v_add_co_u32_e32 v4, vcc, s69, v134
	global_load_dwordx4 v[14:17], v[134:135], off
	global_load_dwordx4 v[18:21], v[136:137], off
	v_addc_co_u32_e32 v5, vcc, 0, v135, vcc
	global_load_dwordx4 v[22:25], v[4:5], off
	v_add_co_u32_e32 v4, vcc, s69, v136
	v_and_b32_e32 v47, 31, v48
	s_nop 0
	v_addc_co_u32_e32 v5, vcc, 0, v137, vcc
	global_load_dwordx4 v[26:29], v[4:5], off
	v_add_co_u32_e32 v4, vcc, s65, v134
	v_lshrrev_b32_e32 v50, 1, v48
	s_nop 0
	v_addc_co_u32_e32 v5, vcc, 0, v135, vcc
	global_load_dwordx4 v[30:33], v[4:5], off
	v_add_co_u32_e32 v4, vcc, s65, v136
	s_mov_b32 s20, 0xfffffc0
	s_nop 0
	v_addc_co_u32_e32 v5, vcc, 0, v137, vcc
	global_load_dwordx4 v[34:37], v[4:5], off
	v_add_co_u32_e32 v4, vcc, s67, v136
	v_and_b32_e32 v51, 0x5f, v48
	s_nop 0
	v_addc_co_u32_e32 v5, vcc, 0, v137, vcc
	global_load_dwordx4 v[38:41], v[4:5], off
	v_add_co_u32_e32 v4, vcc, s67, v134
	v_and_or_b32 v47, v50, s20, v47
	s_nop 0
	v_addc_co_u32_e32 v5, vcc, 0, v135, vcc
	global_load_dwordx4 v[42:45], v[4:5], off
	v_lshl_add_u64 v[196:197], s[22:23], 0, v[132:133]
	v_lshl_add_u64 v[196:197], s[8:9], 1, v[196:197]
	v_lshl_add_u64 v[196:197], v[0:1], 1, v[196:197]
	v_lshl_add_u64 v[196:197], v[196:197], 0, v[2:3]
	v_add_co_u32_e32 v208, vcc, 0x10000, v196
	s_nop 1
	v_addc_co_u32_e32 v209, vcc, 0, v197, vcc
	global_load_dwordx2 v[222:223], v[196:197], off
	global_load_dwordx2 v[224:225], v[196:197], off offset:16
	global_load_dwordx2 v[226:227], v[196:197], off offset:32
	global_load_dwordx2 v[228:229], v[196:197], off offset:48
	global_load_dwordx2 v[230:231], v[208:209], off
	global_load_dwordx2 v[232:233], v[208:209], off offset:16
	global_load_dwordx2 v[234:235], v[208:209], off offset:32
	global_load_dwordx2 v[236:237], v[208:209], off offset:48
	global_load_dwordx2 v[238:239], v[196:197], off offset:64
	global_load_dwordx2 v[240:241], v[196:197], off offset:80
	global_load_dwordx2 v[242:243], v[196:197], off offset:96
	global_load_dwordx2 v[244:245], v[196:197], off offset:112
	global_load_dwordx2 v[246:247], v[208:209], off offset:64
	global_load_dwordx2 v[248:249], v[208:209], off offset:80
	global_load_dwordx2 v[250:251], v[208:209], off offset:96
	global_load_dwordx2 v[252:253], v[208:209], off offset:112
	v_and_b32_e32 v48, 16, v50
	v_mad_u64_u32 v[154:155], s[20:21], v47, s74, v[48:49]
	v_mul_lo_u32 v46, v46, s74
	v_lshlrev_b32_e32 v47, 4, v49
	v_add3_u32 v156, s3, v46, v47
	s_mov_b64 s[14:15], 0
	s_mov_b32 s19, 0
	v_mov_b32_e32 v4, 0
	v_mov_b32_e32 v5, v167
	v_mov_b32_e32 v6, v167
	v_mov_b32_e32 v7, v167
	v_mov_b32_e32 v8, v167
	v_mov_b32_e32 v9, v167
	v_mov_b32_e32 v11, v167
	v_mov_b32_e32 v12, v167
	v_mov_b32_e32 v13, v167
	v_mad_u32_u24 v155, v51, s74, v48
	v_mov_b32_e32 v46, v167
	v_mov_b32_e32 v47, v167
	v_mov_b32_e32 v48, v167
	v_mov_b32_e32 v49, v167
	v_mov_b32_e32 v50, v167
	v_mov_b32_e32 v51, v167
	v_mov_b32_e32 v52, 0
	v_mov_b32_e32 v53, v167
	v_mov_b32_e32 v54, v167
	v_mov_b32_e32 v55, v167
	v_mov_b32_e32 v56, v167
	v_mov_b32_e32 v57, v167
	v_mov_b32_e32 v58, v167
	s_waitcnt vmcnt(22)
	ds_write_b128 v156, v[18:21] offset:18432
	ds_write_b128 v156, v[14:17]
	s_waitcnt vmcnt(20)
	ds_write_b128 v156, v[26:29] offset:23040
	s_waitcnt vmcnt(18)
	ds_write_b128 v156, v[34:37] offset:27648
	s_waitcnt vmcnt(17)
	ds_write_b128 v156, v[38:41] offset:32256
	ds_write_b128 v156, v[22:25] offset:4608
	ds_write_b128 v156, v[30:33] offset:9216
	s_waitcnt vmcnt(16)
	ds_write_b128 v156, v[42:45] offset:13824
	v_mov_b32_e32 v14, v167
	v_mov_b32_e32 v15, v167
	v_mov_b32_e32 v16, v167
	v_mov_b32_e32 v17, v167
	v_mov_b32_e32 v18, v167
	v_mov_b32_e32 v19, v167
	v_mov_b32_e32 v20, 0
	v_mov_b32_e32 v21, v167
	v_mov_b32_e32 v22, v167
	v_mov_b32_e32 v23, v167
	v_mov_b32_e32 v24, v167
	v_mov_b32_e32 v25, v167
	v_mov_b32_e32 v26, v167
	v_mov_b32_e32 v27, v167
	v_mov_b32_e32 v28, v167
	v_mov_b32_e32 v29, v167
	v_mov_b32_e32 v30, v167
	v_mov_b32_e32 v31, v167
	v_mov_b32_e32 v32, v167
	v_mov_b32_e32 v33, v167
	v_mov_b32_e32 v34, v167
	v_mov_b32_e32 v35, v167
	v_mov_b32_e32 v36, 0
	v_mov_b32_e32 v37, v167
	v_mov_b32_e32 v38, v167
	v_mov_b32_e32 v39, v167
	v_mov_b32_e32 v40, v167
	v_mov_b32_e32 v41, v167
	v_mov_b32_e32 v42, v167
	v_mov_b32_e32 v43, v167
	v_mov_b32_e32 v44, v167
	v_mov_b32_e32 v45, v167
	v_mov_b32_e32 v59, v167
	v_mov_b32_e32 v60, v167
	v_mov_b32_e32 v61, v167
	v_mov_b32_e32 v62, v167
	v_mov_b32_e32 v63, v167
	v_mov_b32_e32 v64, v167
	v_mov_b32_e32 v65, v167
	v_mov_b32_e32 v66, v167
	v_mov_b32_e32 v67, v167
	s_waitcnt lgkmcnt(0)
	s_barrier
